# attention O epilogue: wave-private LDS transpose, 8 dwordx4 stores per lane instead of 64 short stores
# baseline (speedup 1.0000x reference)
.LBB0_2054:
	s_or_b64 exec, exec, s[6:7]
	s_waitcnt lgkmcnt(0)
	ds_read_b128 v[66:69], v198
	ds_read_b128 v[70:73], v198 offset:32
	s_lshl_b64 s[6:7], s[30:31], 11
	v_readlane_b32 s10, v255, 11
	s_add_u32 s6, s48, s6
	s_waitcnt lgkmcnt(1)
	v_rcp_f32_e32 v74, v66
	v_rcp_f32_e32 v75, v67
	v_rcp_f32_e32 v76, v68
	v_rcp_f32_e32 v77, v69
	ds_read_b128 v[66:69], v198 offset:64
	v_readlane_b32 s11, v255, 12
	s_addc_u32 s7, s11, s7
	s_lshl_b32 s9, s50, 1
	s_add_u32 s6, s6, s9
	s_addc_u32 s7, s7, 0
	s_waitcnt lgkmcnt(1)
	v_rcp_f32_e32 v78, v70
	v_rcp_f32_e32 v79, v71
	v_rcp_f32_e32 v80, v72
	v_rcp_f32_e32 v81, v73
	ds_read_b128 v[70:73], v198 offset:96
	s_waitcnt lgkmcnt(1)
	v_rcp_f32_e32 v82, v66
	v_rcp_f32_e32 v83, v67
	v_lshl_add_u64 v[66:67], s[6:7], 0, v[178:179]
	v_mov_b32_e32 v191, v179
	v_mul_f32_e32 v2, v2, v74
	v_lshl_add_u64 v[66:67], v[66:67], 0, v[190:191]
	v_bfe_u32 v84, v2, 16, 1
	v_lshl_add_u64 v[66:67], v[66:67], 0, v[180:181]
	v_add3_u32 v2, v2, v84, s41
	v_readlane_b32 s100, v255, 6
	v_and_b32_e32 v130, 63, v0
	v_lshrrev_b32_e32 v131, 5, v130
	v_and_b32_e32 v132, 31, v130
	s_mul_i32 s100, s100, 0x2200
	s_add_i32 s100, s100, 0x12000
	v_mul_u32_u24_e32 v133, 0x440, v131
	v_lshl_add_u32 v133, v132, 1, v133
	v_add_u32_e32 v133, s100, v133
	v_lshrrev_b32_e32 v134, 4, v130
	v_and_b32_e32 v135, 15, v130
	v_mul_u32_u24_e32 v136, 0x110, v134
	v_lshl_add_u32 v136, v135, 4, v136
	v_add_u32_e32 v136, s100, v136
	v_lshlrev_b32_e32 v137, 11, v134
	v_lshl_add_u32 v137, v135, 4, v137
	v_lshlrev_b32_e32 v138, 13, v131
	v_lshl_add_u32 v138, v132, 1, v138
	v_sub_co_u32_e32 v139, vcc, v66, v138
	s_nop 1
	v_subbrev_co_u32_e32 v140, vcc, 0, v67, vcc
	s_nop 1
	v_readfirstlane_b32 s100, v139
	v_readfirstlane_b32 s101, v140
	ds_write_b16_d16_hi v133, v2 offset:0
	v_mul_f32_e32 v2, v50, v74
	v_bfe_u32 v50, v2, 16, 1
	v_add3_u32 v2, v2, v50, s41
	ds_write_b16_d16_hi v133, v2 offset:64
	v_mul_f32_e32 v2, v34, v74
	v_bfe_u32 v34, v2, 16, 1
	v_add3_u32 v2, v2, v34, s41
	ds_write_b16_d16_hi v133, v2 offset:128
	v_mul_f32_e32 v2, v18, v74
	v_bfe_u32 v18, v2, 16, 1
	v_add3_u32 v2, v2, v18, s41
	ds_write_b16_d16_hi v133, v2 offset:192
	v_mul_f32_e32 v2, v3, v75
	v_bfe_u32 v3, v2, 16, 1
	v_add3_u32 v2, v2, v3, s41
	ds_write_b16_d16_hi v133, v2 offset:272
	v_mul_f32_e32 v2, v51, v75
	v_bfe_u32 v3, v2, 16, 1
	v_add3_u32 v2, v2, v3, s41
	ds_write_b16_d16_hi v133, v2 offset:336
	v_mul_f32_e32 v2, v35, v75
	v_bfe_u32 v3, v2, 16, 1
	v_add3_u32 v2, v2, v3, s41
	ds_write_b16_d16_hi v133, v2 offset:400
	v_mul_f32_e32 v2, v19, v75
	v_bfe_u32 v3, v2, 16, 1
	v_add3_u32 v2, v2, v3, s41
	ds_write_b16_d16_hi v133, v2 offset:464
	v_mul_f32_e32 v2, v4, v76
	v_bfe_u32 v3, v2, 16, 1
	v_add3_u32 v4, v2, v3, s41
	v_add_co_u32_e32 v2, vcc, s42, v66
	v_rcp_f32_e32 v68, v68
	s_nop 0
	v_addc_co_u32_e32 v3, vcc, 0, v67, vcc
	ds_write_b16_d16_hi v133, v4 offset:544
	v_mul_f32_e32 v4, v52, v76
	v_bfe_u32 v18, v4, 16, 1
	v_add3_u32 v4, v4, v18, s41
	ds_write_b16_d16_hi v133, v4 offset:608
	v_mul_f32_e32 v4, v36, v76
	v_bfe_u32 v18, v4, 16, 1
	v_add3_u32 v4, v4, v18, s41
	ds_write_b16_d16_hi v133, v4 offset:672
	v_mul_f32_e32 v4, v20, v76
	v_bfe_u32 v18, v4, 16, 1
	v_add3_u32 v4, v4, v18, s41
	ds_write_b16_d16_hi v133, v4 offset:736
	v_mul_f32_e32 v4, v5, v77
	v_bfe_u32 v5, v4, 16, 1
	v_add3_u32 v4, v4, v5, s41
	ds_write_b16_d16_hi v133, v4 offset:816
	v_mul_f32_e32 v4, v53, v77
	v_bfe_u32 v5, v4, 16, 1
	v_add3_u32 v4, v4, v5, s41
	ds_write_b16_d16_hi v133, v4 offset:880
	v_mul_f32_e32 v4, v37, v77
	v_bfe_u32 v5, v4, 16, 1
	v_add3_u32 v4, v4, v5, s41
	ds_write_b16_d16_hi v133, v4 offset:944
	v_mul_f32_e32 v4, v21, v77
	v_bfe_u32 v5, v4, 16, 1
	v_add3_u32 v4, v4, v5, s41
	ds_write_b16_d16_hi v133, v4 offset:1008
	v_mul_f32_e32 v2, v6, v78
	v_bfe_u32 v3, v2, 16, 1
	v_add3_u32 v6, v2, v3, s41
	v_add_co_u32_e32 v2, vcc, s29, v66
	v_rcp_f32_e32 v69, v69
	s_nop 0
	v_addc_co_u32_e32 v3, vcc, 0, v67, vcc
	v_add_co_u32_e32 v4, vcc, s43, v66
	s_waitcnt lgkmcnt(0)
	v_rcp_f32_e32 v70, v70
	v_addc_co_u32_e32 v5, vcc, 0, v67, vcc
	ds_write_b16_d16_hi v133, v6 offset:2176
	v_mul_f32_e32 v6, v54, v78
	v_bfe_u32 v18, v6, 16, 1
	v_add3_u32 v6, v6, v18, s41
	ds_write_b16_d16_hi v133, v6 offset:2240
	v_mul_f32_e32 v6, v38, v78
	v_bfe_u32 v18, v6, 16, 1
	v_add3_u32 v6, v6, v18, s41
	ds_write_b16_d16_hi v133, v6 offset:2304
	v_mul_f32_e32 v6, v22, v78
	v_bfe_u32 v18, v6, 16, 1
	v_add3_u32 v6, v6, v18, s41
	ds_write_b16_d16_hi v133, v6 offset:2368
	v_mul_f32_e32 v6, v7, v79
	v_bfe_u32 v7, v6, 16, 1
	v_add3_u32 v6, v6, v7, s41
	ds_write_b16_d16_hi v133, v6 offset:2448
	v_mul_f32_e32 v6, v55, v79
	v_bfe_u32 v7, v6, 16, 1
	v_add3_u32 v6, v6, v7, s41
	ds_write_b16_d16_hi v133, v6 offset:2512
	v_mul_f32_e32 v6, v39, v79
	v_bfe_u32 v7, v6, 16, 1
	v_add3_u32 v6, v6, v7, s41
	ds_write_b16_d16_hi v133, v6 offset:2576
	v_mul_f32_e32 v6, v23, v79
	v_bfe_u32 v7, v6, 16, 1
	v_add3_u32 v6, v6, v7, s41
	ds_write_b16_d16_hi v133, v6 offset:2640
	v_mul_f32_e32 v2, v8, v80
	v_bfe_u32 v3, v2, 16, 1
	v_add3_u32 v2, v2, v3, s41
	ds_write_b16_d16_hi v133, v2 offset:2720
	v_mul_f32_e32 v2, v56, v80
	v_bfe_u32 v3, v2, 16, 1
	v_add3_u32 v2, v2, v3, s41
	ds_write_b16_d16_hi v133, v2 offset:2784
	v_mul_f32_e32 v2, v40, v80
	v_bfe_u32 v3, v2, 16, 1
	v_add3_u32 v2, v2, v3, s41
	ds_write_b16_d16_hi v133, v2 offset:2848
	v_mul_f32_e32 v2, v24, v80
	v_bfe_u32 v3, v2, 16, 1
	v_add3_u32 v2, v2, v3, s41
	ds_write_b16_d16_hi v133, v2 offset:2912
	v_mul_f32_e32 v2, v9, v81
	v_bfe_u32 v3, v2, 16, 1
	v_add3_u32 v2, v2, v3, s41
	ds_write_b16_d16_hi v133, v2 offset:2992
	v_mul_f32_e32 v2, v57, v81
	v_bfe_u32 v3, v2, 16, 1
	v_add3_u32 v2, v2, v3, s41
	ds_write_b16_d16_hi v133, v2 offset:3056
	v_mul_f32_e32 v2, v41, v81
	v_bfe_u32 v3, v2, 16, 1
	v_add3_u32 v2, v2, v3, s41
	ds_write_b16_d16_hi v133, v2 offset:3120
	v_mul_f32_e32 v2, v25, v81
	v_bfe_u32 v3, v2, 16, 1
	v_add3_u32 v2, v2, v3, s41
	ds_write_b16_d16_hi v133, v2 offset:3184
	v_mul_f32_e32 v2, v10, v82
	v_bfe_u32 v3, v2, 16, 1
	v_add3_u32 v6, v2, v3, s41
	v_add_co_u32_e32 v2, vcc, s36, v66
	v_rcp_f32_e32 v71, v71
	s_nop 0
	v_addc_co_u32_e32 v3, vcc, 0, v67, vcc
	v_add_co_u32_e32 v4, vcc, s45, v66
	v_rcp_f32_e32 v72, v72
	s_nop 0
	v_addc_co_u32_e32 v5, vcc, 0, v67, vcc
	ds_write_b16_d16_hi v133, v6 offset:4352
	v_mul_f32_e32 v6, v58, v82
	v_bfe_u32 v7, v6, 16, 1
	v_add3_u32 v6, v6, v7, s41
	ds_write_b16_d16_hi v133, v6 offset:4416
	v_mul_f32_e32 v6, v42, v82
	v_bfe_u32 v7, v6, 16, 1
	v_add3_u32 v6, v6, v7, s41
	ds_write_b16_d16_hi v133, v6 offset:4480
	v_mul_f32_e32 v6, v26, v82
	v_bfe_u32 v7, v6, 16, 1
	v_add3_u32 v6, v6, v7, s41
	ds_write_b16_d16_hi v133, v6 offset:4544
	v_mul_f32_e32 v6, v11, v83
	v_bfe_u32 v7, v6, 16, 1
	v_add3_u32 v6, v6, v7, s41
	ds_write_b16_d16_hi v133, v6 offset:4624
	v_mul_f32_e32 v6, v59, v83
	v_bfe_u32 v7, v6, 16, 1
	v_add3_u32 v6, v6, v7, s41
	ds_write_b16_d16_hi v133, v6 offset:4688
	v_mul_f32_e32 v6, v43, v83
	v_bfe_u32 v7, v6, 16, 1
	v_add3_u32 v6, v6, v7, s41
	ds_write_b16_d16_hi v133, v6 offset:4752
	v_mul_f32_e32 v6, v27, v83
	v_bfe_u32 v7, v6, 16, 1
	v_add3_u32 v6, v6, v7, s41
	ds_write_b16_d16_hi v133, v6 offset:4816
	v_mul_f32_e32 v2, v12, v68
	v_bfe_u32 v3, v2, 16, 1
	v_add3_u32 v2, v2, v3, s41
	ds_write_b16_d16_hi v133, v2 offset:4896
	v_mul_f32_e32 v2, v60, v68
	v_bfe_u32 v3, v2, 16, 1
	v_add3_u32 v2, v2, v3, s41
	ds_write_b16_d16_hi v133, v2 offset:4960
	v_mul_f32_e32 v2, v44, v68
	v_bfe_u32 v3, v2, 16, 1
	v_add3_u32 v2, v2, v3, s41
	ds_write_b16_d16_hi v133, v2 offset:5024
	v_mul_f32_e32 v2, v28, v68
	v_bfe_u32 v3, v2, 16, 1
	v_add3_u32 v2, v2, v3, s41
	ds_write_b16_d16_hi v133, v2 offset:5088
	v_mul_f32_e32 v2, v13, v69
	v_bfe_u32 v3, v2, 16, 1
	v_add3_u32 v2, v2, v3, s41
	ds_write_b16_d16_hi v133, v2 offset:5168
	v_mul_f32_e32 v2, v61, v69
	v_bfe_u32 v3, v2, 16, 1
	v_add3_u32 v2, v2, v3, s41
	ds_write_b16_d16_hi v133, v2 offset:5232
	v_mul_f32_e32 v2, v45, v69
	v_bfe_u32 v3, v2, 16, 1
	v_add3_u32 v2, v2, v3, s41
	ds_write_b16_d16_hi v133, v2 offset:5296
	v_mul_f32_e32 v2, v29, v69
	v_bfe_u32 v3, v2, 16, 1
	v_add3_u32 v2, v2, v3, s41
	ds_write_b16_d16_hi v133, v2 offset:5360
	v_mul_f32_e32 v2, v14, v70
	v_bfe_u32 v3, v2, 16, 1
	v_add3_u32 v6, v2, v3, s41
	v_add_co_u32_e32 v2, vcc, s46, v66
	v_rcp_f32_e32 v73, v73
	s_nop 0
	v_addc_co_u32_e32 v3, vcc, 0, v67, vcc
	v_add_co_u32_e32 v4, vcc, s47, v66
	s_add_i32 s49, s49, 1
	s_nop 0
	v_addc_co_u32_e32 v5, vcc, 0, v67, vcc
	ds_write_b16_d16_hi v133, v6 offset:6528
	v_mul_f32_e32 v6, v62, v70
	v_bfe_u32 v7, v6, 16, 1
	v_add3_u32 v6, v6, v7, s41
	ds_write_b16_d16_hi v133, v6 offset:6592
	v_mul_f32_e32 v6, v46, v70
	v_bfe_u32 v7, v6, 16, 1
	v_add3_u32 v6, v6, v7, s41
	ds_write_b16_d16_hi v133, v6 offset:6656
	v_mul_f32_e32 v6, v30, v70
	v_bfe_u32 v7, v6, 16, 1
	v_add3_u32 v6, v6, v7, s41
	ds_write_b16_d16_hi v133, v6 offset:6720
	v_mul_f32_e32 v6, v15, v71
	v_bfe_u32 v7, v6, 16, 1
	v_add3_u32 v6, v6, v7, s41
	ds_write_b16_d16_hi v133, v6 offset:6800
	v_mul_f32_e32 v6, v63, v71
	v_bfe_u32 v7, v6, 16, 1
	v_add3_u32 v6, v6, v7, s41
	ds_write_b16_d16_hi v133, v6 offset:6864
	v_mul_f32_e32 v6, v47, v71
	v_bfe_u32 v7, v6, 16, 1
	v_add3_u32 v6, v6, v7, s41
	ds_write_b16_d16_hi v133, v6 offset:6928
	v_mul_f32_e32 v6, v31, v71
	v_bfe_u32 v7, v6, 16, 1
	v_add3_u32 v6, v6, v7, s41
	ds_write_b16_d16_hi v133, v6 offset:6992
	v_mul_f32_e32 v2, v16, v72
	v_bfe_u32 v3, v2, 16, 1
	v_add3_u32 v2, v2, v3, s41
	ds_write_b16_d16_hi v133, v2 offset:7072
	v_mul_f32_e32 v2, v64, v72
	v_bfe_u32 v3, v2, 16, 1
	v_add3_u32 v2, v2, v3, s41
	ds_write_b16_d16_hi v133, v2 offset:7136
	v_mul_f32_e32 v2, v48, v72
	v_bfe_u32 v3, v2, 16, 1
	v_add3_u32 v2, v2, v3, s41
	ds_write_b16_d16_hi v133, v2 offset:7200
	v_mul_f32_e32 v2, v32, v72
	v_bfe_u32 v3, v2, 16, 1
	v_add3_u32 v2, v2, v3, s41
	ds_write_b16_d16_hi v133, v2 offset:7264
	v_mul_f32_e32 v2, v17, v73
	v_bfe_u32 v3, v2, 16, 1
	v_add3_u32 v2, v2, v3, s41
	ds_write_b16_d16_hi v133, v2 offset:7344
	v_mul_f32_e32 v2, v65, v73
	v_bfe_u32 v3, v2, 16, 1
	v_add3_u32 v2, v2, v3, s41
	ds_write_b16_d16_hi v133, v2 offset:7408
	v_mul_f32_e32 v2, v49, v73
	v_bfe_u32 v3, v2, 16, 1
	v_add3_u32 v2, v2, v3, s41
	ds_write_b16_d16_hi v133, v2 offset:7472
	v_mul_f32_e32 v2, v33, v73
	v_bfe_u32 v3, v2, 16, 1
	s_cmpk_eq_i32 s49, 0x400
	v_add3_u32 v2, v2, v3, s41
	s_cselect_b64 s[10:11], -1, 0
	ds_write_b16_d16_hi v133, v2 offset:7536
	s_waitcnt lgkmcnt(0)
	ds_read_b128 v[144:147], v136
	ds_read_b128 v[148:151], v136 offset:1088
	ds_read_b128 v[152:155], v136 offset:2176
	ds_read_b128 v[156:159], v136 offset:3264
	s_waitcnt lgkmcnt(3)
	global_store_dwordx4 v137, v[144:147], s[100:101]
	v_add_u32_e32 v141, 0x2000, v137
	s_waitcnt lgkmcnt(2)
	global_store_dwordx4 v141, v[148:151], s[100:101]
	v_add_u32_e32 v142, 0x4000, v137
	s_waitcnt lgkmcnt(1)
	global_store_dwordx4 v142, v[152:155], s[100:101]
	v_add_u32_e32 v141, 0x6000, v137
	s_waitcnt lgkmcnt(0)
	global_store_dwordx4 v141, v[156:159], s[100:101]
	s_nop 1
	ds_read_b128 v[144:147], v136 offset:4352
	ds_read_b128 v[148:151], v136 offset:5440
	ds_read_b128 v[152:155], v136 offset:6528
	ds_read_b128 v[156:159], v136 offset:7616
	v_add_u32_e32 v142, 0x8000, v137
	s_waitcnt lgkmcnt(3)
	global_store_dwordx4 v142, v[144:147], s[100:101]
	v_add_u32_e32 v141, 0xa000, v137
	s_waitcnt lgkmcnt(2)
	global_store_dwordx4 v141, v[148:151], s[100:101]
	v_add_u32_e32 v142, 0xc000, v137
	s_waitcnt lgkmcnt(1)
	global_store_dwordx4 v142, v[152:155], s[100:101]
	v_add_u32_e32 v141, 0xe000, v137
	s_waitcnt lgkmcnt(0)
	global_store_dwordx4 v141, v[156:159], s[100:101]
	s_waitcnt vmcnt(63) expcnt(7) lgkmcnt(15)
	s_barrier
